# stack + grid barrier round index from an LDS call counter instead of the float-reciprocal division old/nloc (on v201)
# speedup vs baseline: 1.0037x; 1.0004x over previous
.LBB0_58:
	s_or_b64 exec, exec, s[4:5]
	v_mov_b32_e32 v6, 0x25f50
	ds_read_b32 v7, v6
	s_waitcnt vmcnt(0)
	v_readfirstlane_b32 s4, v5
	s_nop 1
	v_add3_u32 v5, s4, v4, 1
	s_waitcnt lgkmcnt(0)
	v_add_u32_e32 v4, 1, v7
	ds_write_b32 v6, v4
	v_mul_lo_u32 v3, v4, v3
	v_cmp_eq_u32_e32 vcc, v5, v3
	s_and_saveexec_b64 s[4:5], vcc
	s_cbranch_execz .LBB0_61
	s_mov_b64 s[6:7], exec
	v_mbcnt_lo_u32_b32 v3, s6, 0
	buffer_wbl2 sc1
	s_waitcnt lgkmcnt(0)
	s_waitcnt vmcnt(0)
	v_mbcnt_hi_u32_b32 v3, s7, v3
	v_cmp_eq_u32_e32 vcc, 0, v3
	s_and_b64 s[8:9], exec, vcc
	s_mov_b64 exec, s[8:9]
	s_cbranch_execz .LBB0_61
	s_bcnt1_i32_b64 s8, s[6:7]
	s_getpc_b64 s[6:7]
	s_add_u32 s6, s6, g_ctl@rel32@lo+13316
	s_addc_u32 s7, s7, g_ctl@rel32@hi+13324
	v_mov_b32_e32 v3, 0
	v_mov_b32_e32 v5, s8
	global_atomic_add v3, v5, s[6:7]
	global_atomic_add v3, v5, s[6:7] offset:256
	global_atomic_add v3, v5, s[6:7] offset:512
	global_atomic_add v3, v5, s[6:7] offset:768
	global_atomic_add v3, v5, s[6:7] offset:1024
	global_atomic_add v3, v5, s[6:7] offset:1280
	global_atomic_add v3, v5, s[6:7] offset:1536
	global_atomic_add v3, v5, s[6:7] offset:1792
	global_atomic_add v3, v5, s[6:7] offset:2048
	global_atomic_add v3, v5, s[6:7] offset:2304
	global_atomic_add v3, v5, s[6:7] offset:2560
	global_atomic_add v3, v5, s[6:7] offset:2816
	global_atomic_add v3, v5, s[6:7] offset:3072
	global_atomic_add v3, v5, s[6:7] offset:3328
	global_atomic_add v3, v5, s[6:7] offset:3584
	global_atomic_add v3, v5, s[6:7] offset:3840

.LBB0_98:
	s_or_b64 exec, exec, s[2:3]
	v_mov_b32_e32 v6, 0x25f50
	ds_read_b32 v7, v6
	s_waitcnt vmcnt(0)
	v_readfirstlane_b32 s2, v5
	s_nop 1
	v_add3_u32 v5, s2, v4, 1
	s_waitcnt lgkmcnt(0)
	v_add_u32_e32 v4, 1, v7
	ds_write_b32 v6, v4
	v_mul_lo_u32 v3, v4, v3
	v_cmp_eq_u32_e32 vcc, v5, v3
	s_and_saveexec_b64 s[2:3], vcc
	s_cbranch_execz .LBB0_101
	s_mov_b64 s[4:5], exec
	v_mbcnt_lo_u32_b32 v3, s4, 0
	buffer_wbl2 sc1
	s_waitcnt lgkmcnt(0)
	s_waitcnt vmcnt(0)
	v_mbcnt_hi_u32_b32 v3, s5, v3
	v_cmp_eq_u32_e32 vcc, 0, v3
	s_and_b64 s[6:7], exec, vcc
	s_mov_b64 exec, s[6:7]
	s_cbranch_execz .LBB0_101
	s_bcnt1_i32_b64 s6, s[4:5]
	s_getpc_b64 s[4:5]
	s_add_u32 s4, s4, g_ctl@rel32@lo+13316
	s_addc_u32 s5, s5, g_ctl@rel32@hi+13324
	v_mov_b32_e32 v3, 0
	v_mov_b32_e32 v5, s6
	global_atomic_add v3, v5, s[4:5]
	global_atomic_add v3, v5, s[4:5] offset:256
	global_atomic_add v3, v5, s[4:5] offset:512
	global_atomic_add v3, v5, s[4:5] offset:768
	global_atomic_add v3, v5, s[4:5] offset:1024
	global_atomic_add v3, v5, s[4:5] offset:1280
	global_atomic_add v3, v5, s[4:5] offset:1536
	global_atomic_add v3, v5, s[4:5] offset:1792
	global_atomic_add v3, v5, s[4:5] offset:2048
	global_atomic_add v3, v5, s[4:5] offset:2304
	global_atomic_add v3, v5, s[4:5] offset:2560
	global_atomic_add v3, v5, s[4:5] offset:2816
	global_atomic_add v3, v5, s[4:5] offset:3072
	global_atomic_add v3, v5, s[4:5] offset:3328
	global_atomic_add v3, v5, s[4:5] offset:3584
	global_atomic_add v3, v5, s[4:5] offset:3840

.LBB0_771:
	s_or_b64 exec, exec, s[2:3]
	v_mov_b32_e32 v5, 0x25f50
	ds_read_b32 v6, v5
	s_waitcnt vmcnt(0)
	v_readfirstlane_b32 s2, v4
	s_nop 1
	v_add3_u32 v4, s2, v3, 1
	s_waitcnt lgkmcnt(0)
	v_add_u32_e32 v3, 1, v6
	ds_write_b32 v5, v3
	v_mul_lo_u32 v2, v3, v2
	v_cmp_eq_u32_e32 vcc, v4, v2
	s_and_saveexec_b64 s[2:3], vcc
	s_cbranch_execz .LBB0_774
	s_mov_b64 s[4:5], exec
	v_mbcnt_lo_u32_b32 v2, s4, 0
	buffer_wbl2 sc1
	s_waitcnt lgkmcnt(0)
	s_waitcnt vmcnt(0)
	v_mbcnt_hi_u32_b32 v2, s5, v2
	v_cmp_eq_u32_e32 vcc, 0, v2
	s_and_b64 s[6:7], exec, vcc
	s_mov_b64 exec, s[6:7]
	s_cbranch_execz .LBB0_774
	s_bcnt1_i32_b64 s6, s[4:5]
	s_getpc_b64 s[4:5]
	s_add_u32 s4, s4, g_ctl@rel32@lo+13316
	s_addc_u32 s5, s5, g_ctl@rel32@hi+13324
	v_mov_b32_e32 v2, 0
	v_mov_b32_e32 v4, s6
	global_atomic_add v2, v4, s[4:5]
	global_atomic_add v2, v4, s[4:5] offset:256
	global_atomic_add v2, v4, s[4:5] offset:512
	global_atomic_add v2, v4, s[4:5] offset:768
	global_atomic_add v2, v4, s[4:5] offset:1024
	global_atomic_add v2, v4, s[4:5] offset:1280
	global_atomic_add v2, v4, s[4:5] offset:1536
	global_atomic_add v2, v4, s[4:5] offset:1792
	global_atomic_add v2, v4, s[4:5] offset:2048
	global_atomic_add v2, v4, s[4:5] offset:2304
	global_atomic_add v2, v4, s[4:5] offset:2560
	global_atomic_add v2, v4, s[4:5] offset:2816
	global_atomic_add v2, v4, s[4:5] offset:3072
	global_atomic_add v2, v4, s[4:5] offset:3328
	global_atomic_add v2, v4, s[4:5] offset:3584
	global_atomic_add v2, v4, s[4:5] offset:3840
